# P6 epilogue: row sums of squares fetched one unit ahead (no load+vmcnt(0) drain at the epilogue head); packed-f32 epilogue
# baseline (speedup 1.0000x reference)
.LBB0_831:
	s_lshl_b32 s4, s4, 5
	s_and_b32 s11, s4, 0x60
	s_mov_b64 s[4:5], 0x80
	s_add_i32 m0, s19, 0x18000
	v_lshl_add_u64 v[8:9], v[8:9], 0, s[4:5]
	s_lshl_b32 s10, s7, 13
	s_lshl_b32 s12, s11, 7
	s_waitcnt vmcnt(2)
	s_barrier
	global_load_lds_dwordx4 v[8:9], off
	v_lshl_add_u64 v[6:7], v[6:7], 0, s[4:5]
	s_add_i32 m0, s19, 0x1a000
	s_add_i32 s31, s19, 0x8000
	s_add_i32 s34, s19, 0xa000
	global_load_lds_dwordx4 v[6:7], off
	v_lshl_add_u64 v[2:3], v[2:3], 0, s[4:5]
	s_mov_b32 m0, s31
	s_add_u32 s8, s22, 0x40080
	global_load_lds_dwordx4 v[2:3], off
	v_lshl_add_u64 v[2:3], v[4:5], 0, s[4:5]
	s_mov_b32 m0, s34
	s_addc_u32 s9, s23, 0
	global_load_lds_dwordx4 v[2:3], off
	s_add_i32 m0, s19, 0x1c000
	v_lshl_add_u64 v[2:3], s[8:9], 0, v[132:133]
	global_load_lds_dwordx4 v[2:3], off
	v_lshl_add_u64 v[2:3], s[8:9], 0, v[136:137]
	s_add_i32 m0, s19, 0x1e000
	v_cvt_f32_u32_e32 v6, s26
	global_load_lds_dwordx4 v[2:3], off
	v_and_b32_e32 v2, 15, v0
	v_lshl_or_b32 v1, s7, 6, v2
	v_lshlrev_b32_e32 v3, 1, v14
	v_lshlrev_b32_e32 v4, 2, v0
	v_lshlrev_b32_e32 v5, 6, v0
	s_movk_i32 s7, 0x3c0
	v_lshl_or_b32 v2, v2, 6, v3
	v_and_b32_e32 v4, 32, v4
	v_and_or_b32 v3, v5, s7, v3
	v_bitop3_b32 v142, s12, v3, v4 bitop3:0xf6
	v_rcp_iflag_f32_e32 v3, v6
	v_bitop3_b32 v2, v2, s10, v4 bitop3:0xde
	v_lshlrev_b32_e32 v4, 11, v12
	s_cmpk_lt_u32 s6, 0x100
	v_mul_f32_e32 v3, 0x4f7ffffe, v3
	v_cvt_u32_f32_e32 v3, v3
	s_cselect_b64 s[6:7], -1, 0
	s_sub_i32 s8, 0, s26
	s_waitcnt vmcnt(6)
	v_readfirstlane_b32 s9, v3
	v_lshlrev_b32_e32 v3, 8, v0
	v_and_b32_e32 v3, 0x18000, v3
	v_or3_b32 v3, v10, v3, v4
	v_add_u32_e32 v138, v3, v11
	v_lshlrev_b32_e32 v3, 4, v13
	s_mul_i32 s8, s8, s9
	v_and_b32_e32 v3, 0x38000, v3
	s_mul_hi_u32 s8, s9, s8
	v_or3_b32 v3, v10, v3, v4
	s_add_i32 s37, 0, 0x10000
	s_add_i32 s38, 0, 0x14000
	s_add_i32 s35, s26, -1
	v_or_b32_e32 v143, s11, v14
	s_add_i32 s36, s9, s8
	v_mov_b32_e32 v139, v133
	v_add_u32_e32 v140, v3, v11
	v_mov_b32_e32 v141, v133
	v_add_u32_e32 v144, s37, v142
	v_add_u32_e32 v145, s38, v142
	v_add_u32_e32 v146, 0, v2
	v_mov_b32_e32 v147, 0x358637bd
	s_movk_i32 s39, 0x1600
	v_lshl_add_u32 v232, s18, 8, v1
	v_lshlrev_b32_e32 v232, 2, v232
	global_load_dword v224, v232, s[76:77]
	global_load_dword v225, v232, s[76:77] offset:64
	global_load_dword v226, v232, s[76:77] offset:128
	global_load_dword v227, v232, s[76:77] offset:192
	global_load_dword v228, v232, s[76:77] offset:512
	global_load_dword v229, v232, s[76:77] offset:576
	global_load_dword v230, v232, s[76:77] offset:640
	global_load_dword v231, v232, s[76:77] offset:704
	s_barrier
	s_branch .LBB0_834

.LBB0_844:
	s_waitcnt vmcnt(8)
	v_lshl_add_u32 v148, s18, 8, v1
	v_lshl_or_b32 v174, s16, 7, v143
	v_mul_u32_u24_e32 v149, 0x1600, v148
	v_lshl_add_u32 v149, v174, 1, v149
	v_fmamk_f32 v150, v224, 0x3a800000, v147
	v_fmamk_f32 v152, v225, 0x3a800000, v147
	v_fmamk_f32 v154, v226, 0x3a800000, v147
	v_fmamk_f32 v156, v227, 0x3a800000, v147
	v_fmamk_f32 v158, v228, 0x3a800000, v147
	v_fmamk_f32 v160, v229, 0x3a800000, v147
	v_fmamk_f32 v162, v230, 0x3a800000, v147
	v_fmamk_f32 v164, v231, 0x3a800000, v147
	s_min_u32 s20, s10, 64
	v_lshl_add_u32 v232, s20, 8, v1
	v_lshlrev_b32_e32 v232, 2, v232
	global_load_dword v224, v232, s[76:77]
	global_load_dword v225, v232, s[76:77] offset:64
	global_load_dword v226, v232, s[76:77] offset:128
	global_load_dword v227, v232, s[76:77] offset:192
	global_load_dword v228, v232, s[76:77] offset:512
	global_load_dword v229, v232, s[76:77] offset:576
	global_load_dword v230, v232, s[76:77] offset:640
	global_load_dword v231, v232, s[76:77] offset:704
	s_mov_b32 s20, 0xbfb8aa3b
	s_mov_b32 s21, 0xbfb8aa3b
	v_rsq_f32_e32 v150, v150
	v_rsq_f32_e32 v152, v152
	v_rsq_f32_e32 v154, v154
	v_rsq_f32_e32 v156, v156
	v_rsq_f32_e32 v158, v158
	v_rsq_f32_e32 v160, v160
	v_rsq_f32_e32 v162, v162
	v_rsq_f32_e32 v164, v164
	v_pk_mul_f32 v[126:127], v[126:127], v[150:151] op_sel_hi:[1,0]
	v_pk_mul_f32 v[128:129], v[128:129], v[150:151] op_sel_hi:[1,0]
	v_pk_mul_f32 v[122:123], v[122:123], v[150:151] op_sel_hi:[1,0]
	v_pk_mul_f32 v[124:125], v[124:125], v[150:151] op_sel_hi:[1,0]
	v_pk_mul_f32 v[118:119], v[118:119], v[150:151] op_sel_hi:[1,0]
	v_pk_mul_f32 v[120:121], v[120:121], v[150:151] op_sel_hi:[1,0]
	v_pk_mul_f32 v[114:115], v[114:115], v[150:151] op_sel_hi:[1,0]
	v_pk_mul_f32 v[116:117], v[116:117], v[150:151] op_sel_hi:[1,0]
	v_pk_mul_f32 v[166:167], v[126:127], s[20:21]
	v_pk_mul_f32 v[168:169], v[128:129], s[20:21]
	v_pk_mul_f32 v[170:171], v[122:123], s[20:21]
	v_pk_mul_f32 v[172:173], v[124:125], s[20:21]
	v_exp_f32_e32 v166, v166
	v_exp_f32_e32 v167, v167
	v_exp_f32_e32 v168, v168
	v_exp_f32_e32 v169, v169
	v_exp_f32_e32 v170, v170
	v_exp_f32_e32 v171, v171
	v_exp_f32_e32 v172, v172
	v_exp_f32_e32 v173, v173
	v_pk_add_f32 v[166:167], v[166:167], 1.0 op_sel_hi:[1,0]
	v_pk_add_f32 v[168:169], v[168:169], 1.0 op_sel_hi:[1,0]
	v_pk_add_f32 v[170:171], v[170:171], 1.0 op_sel_hi:[1,0]
	v_pk_add_f32 v[172:173], v[172:173], 1.0 op_sel_hi:[1,0]
	v_rcp_f32_e32 v166, v166
	v_rcp_f32_e32 v167, v167
	v_rcp_f32_e32 v168, v168
	v_rcp_f32_e32 v169, v169
	v_rcp_f32_e32 v170, v170
	v_rcp_f32_e32 v171, v171
	v_rcp_f32_e32 v172, v172
	v_rcp_f32_e32 v173, v173
	v_pk_mul_f32 v[126:127], v[126:127], v[118:119]
	v_pk_mul_f32 v[128:129], v[128:129], v[120:121]
	v_pk_mul_f32 v[122:123], v[122:123], v[114:115]
	v_pk_mul_f32 v[124:125], v[124:125], v[116:117]
	v_pk_mul_f32 v[126:127], v[126:127], v[166:167]
	v_pk_mul_f32 v[128:129], v[128:129], v[168:169]
	v_pk_mul_f32 v[122:123], v[122:123], v[170:171]
	v_pk_mul_f32 v[124:125], v[124:125], v[172:173]
	v_cvt_pk_bf16_f32 v126, v126, v127
	v_cvt_pk_bf16_f32 v127, v128, v129
	v_cvt_pk_bf16_f32 v128, v122, v123
	v_cvt_pk_bf16_f32 v129, v124, v125
	global_store_dwordx4 v149, v[126:129], s[92:93]
	v_pk_mul_f32 v[110:111], v[110:111], v[152:153] op_sel_hi:[1,0]
	v_pk_mul_f32 v[112:113], v[112:113], v[152:153] op_sel_hi:[1,0]
	v_pk_mul_f32 v[102:103], v[102:103], v[152:153] op_sel_hi:[1,0]
	v_pk_mul_f32 v[104:105], v[104:105], v[152:153] op_sel_hi:[1,0]
	v_pk_mul_f32 v[106:107], v[106:107], v[152:153] op_sel_hi:[1,0]
	v_pk_mul_f32 v[108:109], v[108:109], v[152:153] op_sel_hi:[1,0]
	v_pk_mul_f32 v[98:99], v[98:99], v[152:153] op_sel_hi:[1,0]
	v_pk_mul_f32 v[100:101], v[100:101], v[152:153] op_sel_hi:[1,0]
	v_pk_mul_f32 v[166:167], v[110:111], s[20:21]
	v_pk_mul_f32 v[168:169], v[112:113], s[20:21]
	v_pk_mul_f32 v[170:171], v[102:103], s[20:21]
	v_pk_mul_f32 v[172:173], v[104:105], s[20:21]
	v_exp_f32_e32 v166, v166
	v_exp_f32_e32 v167, v167
	v_exp_f32_e32 v168, v168
	v_exp_f32_e32 v169, v169
	v_exp_f32_e32 v170, v170
	v_exp_f32_e32 v171, v171
	v_exp_f32_e32 v172, v172
	v_exp_f32_e32 v173, v173
	v_pk_add_f32 v[166:167], v[166:167], 1.0 op_sel_hi:[1,0]
	v_pk_add_f32 v[168:169], v[168:169], 1.0 op_sel_hi:[1,0]
	v_pk_add_f32 v[170:171], v[170:171], 1.0 op_sel_hi:[1,0]
	v_pk_add_f32 v[172:173], v[172:173], 1.0 op_sel_hi:[1,0]
	v_rcp_f32_e32 v166, v166
	v_rcp_f32_e32 v167, v167
	v_rcp_f32_e32 v168, v168
	v_rcp_f32_e32 v169, v169
	v_rcp_f32_e32 v170, v170
	v_rcp_f32_e32 v171, v171
	v_rcp_f32_e32 v172, v172
	v_rcp_f32_e32 v173, v173
	v_pk_mul_f32 v[110:111], v[110:111], v[106:107]
	v_pk_mul_f32 v[112:113], v[112:113], v[108:109]
	v_pk_mul_f32 v[102:103], v[102:103], v[98:99]
	v_pk_mul_f32 v[104:105], v[104:105], v[100:101]
	v_pk_mul_f32 v[110:111], v[110:111], v[166:167]
	v_pk_mul_f32 v[112:113], v[112:113], v[168:169]
	v_pk_mul_f32 v[102:103], v[102:103], v[170:171]
	v_pk_mul_f32 v[104:105], v[104:105], v[172:173]
	v_cvt_pk_bf16_f32 v110, v110, v111
	v_cvt_pk_bf16_f32 v111, v112, v113
	v_cvt_pk_bf16_f32 v112, v102, v103
	v_cvt_pk_bf16_f32 v113, v104, v105
	v_add_u32_e32 v174, 0x16000, v149
	global_store_dwordx4 v174, v[110:113], s[92:93]
	v_pk_mul_f32 v[94:95], v[94:95], v[154:155] op_sel_hi:[1,0]
	v_pk_mul_f32 v[96:97], v[96:97], v[154:155] op_sel_hi:[1,0]
	v_pk_mul_f32 v[86:87], v[86:87], v[154:155] op_sel_hi:[1,0]
	v_pk_mul_f32 v[88:89], v[88:89], v[154:155] op_sel_hi:[1,0]
	v_pk_mul_f32 v[90:91], v[90:91], v[154:155] op_sel_hi:[1,0]
	v_pk_mul_f32 v[92:93], v[92:93], v[154:155] op_sel_hi:[1,0]
	v_pk_mul_f32 v[82:83], v[82:83], v[154:155] op_sel_hi:[1,0]
	v_pk_mul_f32 v[84:85], v[84:85], v[154:155] op_sel_hi:[1,0]
	v_pk_mul_f32 v[166:167], v[94:95], s[20:21]
	v_pk_mul_f32 v[168:169], v[96:97], s[20:21]
	v_pk_mul_f32 v[170:171], v[86:87], s[20:21]
	v_pk_mul_f32 v[172:173], v[88:89], s[20:21]
	v_exp_f32_e32 v166, v166
	v_exp_f32_e32 v167, v167
	v_exp_f32_e32 v168, v168
	v_exp_f32_e32 v169, v169
	v_exp_f32_e32 v170, v170
	v_exp_f32_e32 v171, v171
	v_exp_f32_e32 v172, v172
	v_exp_f32_e32 v173, v173
	v_pk_add_f32 v[166:167], v[166:167], 1.0 op_sel_hi:[1,0]
	v_pk_add_f32 v[168:169], v[168:169], 1.0 op_sel_hi:[1,0]
	v_pk_add_f32 v[170:171], v[170:171], 1.0 op_sel_hi:[1,0]
	v_pk_add_f32 v[172:173], v[172:173], 1.0 op_sel_hi:[1,0]
	v_rcp_f32_e32 v166, v166
	v_rcp_f32_e32 v167, v167
	v_rcp_f32_e32 v168, v168
	v_rcp_f32_e32 v169, v169
	v_rcp_f32_e32 v170, v170
	v_rcp_f32_e32 v171, v171
	v_rcp_f32_e32 v172, v172
	v_rcp_f32_e32 v173, v173
	v_pk_mul_f32 v[94:95], v[94:95], v[90:91]
	v_pk_mul_f32 v[96:97], v[96:97], v[92:93]
	v_pk_mul_f32 v[86:87], v[86:87], v[82:83]
	v_pk_mul_f32 v[88:89], v[88:89], v[84:85]
	v_pk_mul_f32 v[94:95], v[94:95], v[166:167]
	v_pk_mul_f32 v[96:97], v[96:97], v[168:169]
	v_pk_mul_f32 v[86:87], v[86:87], v[170:171]
	v_pk_mul_f32 v[88:89], v[88:89], v[172:173]
	v_cvt_pk_bf16_f32 v94, v94, v95
	v_cvt_pk_bf16_f32 v95, v96, v97
	v_cvt_pk_bf16_f32 v96, v86, v87
	v_cvt_pk_bf16_f32 v97, v88, v89
	v_add_u32_e32 v174, 0x2c000, v149
	global_store_dwordx4 v174, v[94:97], s[92:93]
	v_pk_mul_f32 v[78:79], v[78:79], v[156:157] op_sel_hi:[1,0]
	v_pk_mul_f32 v[80:81], v[80:81], v[156:157] op_sel_hi:[1,0]
	v_pk_mul_f32 v[70:71], v[70:71], v[156:157] op_sel_hi:[1,0]
	v_pk_mul_f32 v[72:73], v[72:73], v[156:157] op_sel_hi:[1,0]
	v_pk_mul_f32 v[74:75], v[74:75], v[156:157] op_sel_hi:[1,0]
	v_pk_mul_f32 v[76:77], v[76:77], v[156:157] op_sel_hi:[1,0]
	v_pk_mul_f32 v[66:67], v[66:67], v[156:157] op_sel_hi:[1,0]
	v_pk_mul_f32 v[68:69], v[68:69], v[156:157] op_sel_hi:[1,0]
	v_pk_mul_f32 v[166:167], v[78:79], s[20:21]
	v_pk_mul_f32 v[168:169], v[80:81], s[20:21]
	v_pk_mul_f32 v[170:171], v[70:71], s[20:21]
	v_pk_mul_f32 v[172:173], v[72:73], s[20:21]
	v_exp_f32_e32 v166, v166
	v_exp_f32_e32 v167, v167
	v_exp_f32_e32 v168, v168
	v_exp_f32_e32 v169, v169
	v_exp_f32_e32 v170, v170
	v_exp_f32_e32 v171, v171
	v_exp_f32_e32 v172, v172
	v_exp_f32_e32 v173, v173
	v_pk_add_f32 v[166:167], v[166:167], 1.0 op_sel_hi:[1,0]
	v_pk_add_f32 v[168:169], v[168:169], 1.0 op_sel_hi:[1,0]
	v_pk_add_f32 v[170:171], v[170:171], 1.0 op_sel_hi:[1,0]
	v_pk_add_f32 v[172:173], v[172:173], 1.0 op_sel_hi:[1,0]
	v_rcp_f32_e32 v166, v166
	v_rcp_f32_e32 v167, v167
	v_rcp_f32_e32 v168, v168
	v_rcp_f32_e32 v169, v169
	v_rcp_f32_e32 v170, v170
	v_rcp_f32_e32 v171, v171
	v_rcp_f32_e32 v172, v172
	v_rcp_f32_e32 v173, v173
	v_pk_mul_f32 v[78:79], v[78:79], v[74:75]
	v_pk_mul_f32 v[80:81], v[80:81], v[76:77]
	v_pk_mul_f32 v[70:71], v[70:71], v[66:67]
	v_pk_mul_f32 v[72:73], v[72:73], v[68:69]
	v_pk_mul_f32 v[78:79], v[78:79], v[166:167]
	v_pk_mul_f32 v[80:81], v[80:81], v[168:169]
	v_pk_mul_f32 v[70:71], v[70:71], v[170:171]
	v_pk_mul_f32 v[72:73], v[72:73], v[172:173]
	v_cvt_pk_bf16_f32 v78, v78, v79
	v_cvt_pk_bf16_f32 v79, v80, v81
	v_cvt_pk_bf16_f32 v80, v70, v71
	v_cvt_pk_bf16_f32 v81, v72, v73
	v_add_u32_e32 v174, 0x42000, v149
	global_store_dwordx4 v174, v[78:81], s[92:93]
	v_pk_mul_f32 v[62:63], v[62:63], v[158:159] op_sel_hi:[1,0]
	v_pk_mul_f32 v[64:65], v[64:65], v[158:159] op_sel_hi:[1,0]
	v_pk_mul_f32 v[54:55], v[54:55], v[158:159] op_sel_hi:[1,0]
	v_pk_mul_f32 v[56:57], v[56:57], v[158:159] op_sel_hi:[1,0]
	v_pk_mul_f32 v[58:59], v[58:59], v[158:159] op_sel_hi:[1,0]
	v_pk_mul_f32 v[60:61], v[60:61], v[158:159] op_sel_hi:[1,0]
	v_pk_mul_f32 v[50:51], v[50:51], v[158:159] op_sel_hi:[1,0]
	v_pk_mul_f32 v[52:53], v[52:53], v[158:159] op_sel_hi:[1,0]
	v_pk_mul_f32 v[166:167], v[62:63], s[20:21]
	v_pk_mul_f32 v[168:169], v[64:65], s[20:21]
	v_pk_mul_f32 v[170:171], v[54:55], s[20:21]
	v_pk_mul_f32 v[172:173], v[56:57], s[20:21]
	v_exp_f32_e32 v166, v166
	v_exp_f32_e32 v167, v167
	v_exp_f32_e32 v168, v168
	v_exp_f32_e32 v169, v169
	v_exp_f32_e32 v170, v170
	v_exp_f32_e32 v171, v171
	v_exp_f32_e32 v172, v172
	v_exp_f32_e32 v173, v173
	v_pk_add_f32 v[166:167], v[166:167], 1.0 op_sel_hi:[1,0]
	v_pk_add_f32 v[168:169], v[168:169], 1.0 op_sel_hi:[1,0]
	v_pk_add_f32 v[170:171], v[170:171], 1.0 op_sel_hi:[1,0]
	v_pk_add_f32 v[172:173], v[172:173], 1.0 op_sel_hi:[1,0]
	v_rcp_f32_e32 v166, v166
	v_rcp_f32_e32 v167, v167
	v_rcp_f32_e32 v168, v168
	v_rcp_f32_e32 v169, v169
	v_rcp_f32_e32 v170, v170
	v_rcp_f32_e32 v171, v171
	v_rcp_f32_e32 v172, v172
	v_rcp_f32_e32 v173, v173
	v_pk_mul_f32 v[62:63], v[62:63], v[58:59]
	v_pk_mul_f32 v[64:65], v[64:65], v[60:61]
	v_pk_mul_f32 v[54:55], v[54:55], v[50:51]
	v_pk_mul_f32 v[56:57], v[56:57], v[52:53]
	v_pk_mul_f32 v[62:63], v[62:63], v[166:167]
	v_pk_mul_f32 v[64:65], v[64:65], v[168:169]
	v_pk_mul_f32 v[54:55], v[54:55], v[170:171]
	v_pk_mul_f32 v[56:57], v[56:57], v[172:173]
	v_cvt_pk_bf16_f32 v62, v62, v63
	v_cvt_pk_bf16_f32 v63, v64, v65
	v_cvt_pk_bf16_f32 v64, v54, v55
	v_cvt_pk_bf16_f32 v65, v56, v57
	v_add_u32_e32 v174, 0xb0000, v149
	global_store_dwordx4 v174, v[62:65], s[92:93]
	v_pk_mul_f32 v[46:47], v[46:47], v[160:161] op_sel_hi:[1,0]
	v_pk_mul_f32 v[48:49], v[48:49], v[160:161] op_sel_hi:[1,0]
	v_pk_mul_f32 v[38:39], v[38:39], v[160:161] op_sel_hi:[1,0]
	v_pk_mul_f32 v[40:41], v[40:41], v[160:161] op_sel_hi:[1,0]
	v_pk_mul_f32 v[42:43], v[42:43], v[160:161] op_sel_hi:[1,0]
	v_pk_mul_f32 v[44:45], v[44:45], v[160:161] op_sel_hi:[1,0]
	v_pk_mul_f32 v[34:35], v[34:35], v[160:161] op_sel_hi:[1,0]
	v_pk_mul_f32 v[36:37], v[36:37], v[160:161] op_sel_hi:[1,0]
	v_pk_mul_f32 v[166:167], v[46:47], s[20:21]
	v_pk_mul_f32 v[168:169], v[48:49], s[20:21]
	v_pk_mul_f32 v[170:171], v[38:39], s[20:21]
	v_pk_mul_f32 v[172:173], v[40:41], s[20:21]
	v_exp_f32_e32 v166, v166
	v_exp_f32_e32 v167, v167
	v_exp_f32_e32 v168, v168
	v_exp_f32_e32 v169, v169
	v_exp_f32_e32 v170, v170
	v_exp_f32_e32 v171, v171
	v_exp_f32_e32 v172, v172
	v_exp_f32_e32 v173, v173
	v_pk_add_f32 v[166:167], v[166:167], 1.0 op_sel_hi:[1,0]
	v_pk_add_f32 v[168:169], v[168:169], 1.0 op_sel_hi:[1,0]
	v_pk_add_f32 v[170:171], v[170:171], 1.0 op_sel_hi:[1,0]
	v_pk_add_f32 v[172:173], v[172:173], 1.0 op_sel_hi:[1,0]
	v_rcp_f32_e32 v166, v166
	v_rcp_f32_e32 v167, v167
	v_rcp_f32_e32 v168, v168
	v_rcp_f32_e32 v169, v169
	v_rcp_f32_e32 v170, v170
	v_rcp_f32_e32 v171, v171
	v_rcp_f32_e32 v172, v172
	v_rcp_f32_e32 v173, v173
	v_pk_mul_f32 v[46:47], v[46:47], v[42:43]
	v_pk_mul_f32 v[48:49], v[48:49], v[44:45]
	v_pk_mul_f32 v[38:39], v[38:39], v[34:35]
	v_pk_mul_f32 v[40:41], v[40:41], v[36:37]
	v_pk_mul_f32 v[46:47], v[46:47], v[166:167]
	v_pk_mul_f32 v[48:49], v[48:49], v[168:169]
	v_pk_mul_f32 v[38:39], v[38:39], v[170:171]
	v_pk_mul_f32 v[40:41], v[40:41], v[172:173]
	v_cvt_pk_bf16_f32 v46, v46, v47
	v_cvt_pk_bf16_f32 v47, v48, v49
	v_cvt_pk_bf16_f32 v48, v38, v39
	v_cvt_pk_bf16_f32 v49, v40, v41
	v_add_u32_e32 v174, 0xc6000, v149
	global_store_dwordx4 v174, v[46:49], s[92:93]
	v_pk_mul_f32 v[30:31], v[30:31], v[162:163] op_sel_hi:[1,0]
	v_pk_mul_f32 v[32:33], v[32:33], v[162:163] op_sel_hi:[1,0]
	v_pk_mul_f32 v[22:23], v[22:23], v[162:163] op_sel_hi:[1,0]
	v_pk_mul_f32 v[24:25], v[24:25], v[162:163] op_sel_hi:[1,0]
	v_pk_mul_f32 v[26:27], v[26:27], v[162:163] op_sel_hi:[1,0]
	v_pk_mul_f32 v[28:29], v[28:29], v[162:163] op_sel_hi:[1,0]
	v_pk_mul_f32 v[18:19], v[18:19], v[162:163] op_sel_hi:[1,0]
	v_pk_mul_f32 v[20:21], v[20:21], v[162:163] op_sel_hi:[1,0]
	v_pk_mul_f32 v[166:167], v[30:31], s[20:21]
	v_pk_mul_f32 v[168:169], v[32:33], s[20:21]
	v_pk_mul_f32 v[170:171], v[22:23], s[20:21]
	v_pk_mul_f32 v[172:173], v[24:25], s[20:21]
	v_exp_f32_e32 v166, v166
	v_exp_f32_e32 v167, v167
	v_exp_f32_e32 v168, v168
	v_exp_f32_e32 v169, v169
	v_exp_f32_e32 v170, v170
	v_exp_f32_e32 v171, v171
	v_exp_f32_e32 v172, v172
	v_exp_f32_e32 v173, v173
	v_pk_add_f32 v[166:167], v[166:167], 1.0 op_sel_hi:[1,0]
	v_pk_add_f32 v[168:169], v[168:169], 1.0 op_sel_hi:[1,0]
	v_pk_add_f32 v[170:171], v[170:171], 1.0 op_sel_hi:[1,0]
	v_pk_add_f32 v[172:173], v[172:173], 1.0 op_sel_hi:[1,0]
	v_rcp_f32_e32 v166, v166
	v_rcp_f32_e32 v167, v167
	v_rcp_f32_e32 v168, v168
	v_rcp_f32_e32 v169, v169
	v_rcp_f32_e32 v170, v170
	v_rcp_f32_e32 v171, v171
	v_rcp_f32_e32 v172, v172
	v_rcp_f32_e32 v173, v173
	v_pk_mul_f32 v[30:31], v[30:31], v[26:27]
	v_pk_mul_f32 v[32:33], v[32:33], v[28:29]
	v_pk_mul_f32 v[22:23], v[22:23], v[18:19]
	v_pk_mul_f32 v[24:25], v[24:25], v[20:21]
	v_pk_mul_f32 v[30:31], v[30:31], v[166:167]
	v_pk_mul_f32 v[32:33], v[32:33], v[168:169]
	v_pk_mul_f32 v[22:23], v[22:23], v[170:171]
	v_pk_mul_f32 v[24:25], v[24:25], v[172:173]
	v_cvt_pk_bf16_f32 v30, v30, v31
	v_cvt_pk_bf16_f32 v31, v32, v33
	v_cvt_pk_bf16_f32 v32, v22, v23
	v_cvt_pk_bf16_f32 v33, v24, v25
	v_add_u32_e32 v174, 0xdc000, v149
	global_store_dwordx4 v174, v[30:33], s[92:93]
	v_pk_mul_f32 v[14:15], v[14:15], v[164:165] op_sel_hi:[1,0]
	v_pk_mul_f32 v[16:17], v[16:17], v[164:165] op_sel_hi:[1,0]
	v_pk_mul_f32 v[6:7], v[6:7], v[164:165] op_sel_hi:[1,0]
	v_pk_mul_f32 v[8:9], v[8:9], v[164:165] op_sel_hi:[1,0]
	v_pk_mul_f32 v[10:11], v[10:11], v[164:165] op_sel_hi:[1,0]
	v_pk_mul_f32 v[12:13], v[12:13], v[164:165] op_sel_hi:[1,0]
	v_pk_mul_f32 v[2:3], v[2:3], v[164:165] op_sel_hi:[1,0]
	v_pk_mul_f32 v[4:5], v[4:5], v[164:165] op_sel_hi:[1,0]
	v_pk_mul_f32 v[166:167], v[14:15], s[20:21]
	v_pk_mul_f32 v[168:169], v[16:17], s[20:21]
	v_pk_mul_f32 v[170:171], v[6:7], s[20:21]
	v_pk_mul_f32 v[172:173], v[8:9], s[20:21]
	v_exp_f32_e32 v166, v166
	v_exp_f32_e32 v167, v167
	v_exp_f32_e32 v168, v168
	v_exp_f32_e32 v169, v169
	v_exp_f32_e32 v170, v170
	v_exp_f32_e32 v171, v171
	v_exp_f32_e32 v172, v172
	v_exp_f32_e32 v173, v173
	v_pk_add_f32 v[166:167], v[166:167], 1.0 op_sel_hi:[1,0]
	v_pk_add_f32 v[168:169], v[168:169], 1.0 op_sel_hi:[1,0]
	v_pk_add_f32 v[170:171], v[170:171], 1.0 op_sel_hi:[1,0]
	v_pk_add_f32 v[172:173], v[172:173], 1.0 op_sel_hi:[1,0]
	v_rcp_f32_e32 v166, v166
	v_rcp_f32_e32 v167, v167
	v_rcp_f32_e32 v168, v168
	v_rcp_f32_e32 v169, v169
	v_rcp_f32_e32 v170, v170
	v_rcp_f32_e32 v171, v171
	v_rcp_f32_e32 v172, v172
	v_rcp_f32_e32 v173, v173
	v_pk_mul_f32 v[14:15], v[14:15], v[10:11]
	v_pk_mul_f32 v[16:17], v[16:17], v[12:13]
	v_pk_mul_f32 v[6:7], v[6:7], v[2:3]
	v_pk_mul_f32 v[8:9], v[8:9], v[4:5]
	v_pk_mul_f32 v[14:15], v[14:15], v[166:167]
	v_pk_mul_f32 v[16:17], v[16:17], v[168:169]
	v_pk_mul_f32 v[6:7], v[6:7], v[170:171]
	v_pk_mul_f32 v[8:9], v[8:9], v[172:173]
	v_cvt_pk_bf16_f32 v14, v14, v15
	v_cvt_pk_bf16_f32 v15, v16, v17
	v_cvt_pk_bf16_f32 v16, v6, v7
	v_cvt_pk_bf16_f32 v17, v8, v9
	v_add_u32_e32 v174, 0xf2000, v149
	global_store_dwordx4 v174, v[14:17], s[92:93]
	s_cmp_eq_u32 s17, s35
	s_mov_b64 s[16:17], -1
	s_cbranch_scc1 .LBB0_833
	s_andn2_b64 vcc, exec, s[2:3]
	s_cbranch_vccnz .LBB0_832
	s_barrier
	s_branch .LBB0_832
